# lora w-branch epilogue: -exp(-softplus(z)-0.5) evaluated in the algebraically identical form -exp(-0.5)*sigmoid(-z) (exp+rcp instead of exp+log+exp), f32 throughout
# speedup vs baseline: 1.0231x; 1.0030x over previous
.LBB0_302:
	global_load_dwordx4 v[12:15], v[4:5], off
	v_add_u32_e32 v0, s6, v109
	ds_read_b128 v[8:11], v0
	v_ashrrev_i32_e32 v71, 31, v70
	v_ashrrev_i32_e32 v69, 31, v68
	v_ashrrev_i32_e32 v67, 31, v66
	v_ashrrev_i32_e32 v65, 31, v64
	s_waitcnt vmcnt(0) lgkmcnt(0)
	v_add_f32_e32 v0, v8, v12
	v_mul_f32_e32 v1, 0xbfb8aa3b, v0
	v_exp_f32_e32 v1, v1
	s_nop 0
	v_add_f32_e32 v1, 1.0, v1
	v_rcp_f32_e32 v1, v1
	s_nop 0
	s_nop 0
	s_nop 1
	s_nop 0
	s_nop 1
	v_mul_f32_e32 v0, 0x3f1b4598, v1
	v_add_f32_e32 v1, v9, v13
	v_mul_f32_e32 v2, 0xbfb8aa3b, v1
	v_exp_f32_e32 v2, v2
	s_nop 0
	v_add_f32_e32 v2, 1.0, v2
	v_rcp_f32_e32 v2, v2
	s_nop 0
	s_nop 1
	s_nop 0
	s_nop 1
	v_mul_f32_e32 v1, 0x3f1b4598, v2
	v_mov_b32_e32 v2, v1
	v_add_f32_e32 v1, v10, v14
	v_mul_f32_e32 v3, 0xbfb8aa3b, v1
	v_exp_f32_e32 v3, v3
	s_nop 0
	v_add_f32_e32 v3, 1.0, v3
	v_rcp_f32_e32 v3, v3
	s_nop 0
	s_nop 0
	s_nop 1
	s_nop 0
	s_nop 1
	v_mul_f32_e32 v1, 0x3f1b4598, v3
	v_add_f32_e32 v3, v11, v15
	v_mul_f32_e32 v8, 0xbfb8aa3b, v3
	v_exp_f32_e32 v8, v8
	s_nop 0
	v_add_f32_e32 v8, 1.0, v8
	v_rcp_f32_e32 v8, v8
	s_nop 0
	v_pk_add_f32 v[0:1], v[0:1], 0 neg_lo:[1,1] neg_hi:[1,1]
	s_nop 0
	v_and_b32_sdwa v10, v1, v115 dst_sel:DWORD dst_unused:UNUSED_PAD src0_sel:WORD_1 src1_sel:DWORD
	v_and_b32_sdwa v11, v0, v115 dst_sel:DWORD dst_unused:UNUSED_PAD src0_sel:WORD_1 src1_sel:DWORD
	v_add3_u32 v0, v0, v11, s82
	v_add3_u32 v1, v1, v10, s82
	s_nop 0
	v_mul_f32_e32 v3, 0x3f1b4598, v8
	v_lshlrev_b64 v[8:9], 10, v[70:71]
	v_lshl_add_u64 v[8:9], v[6:7], 0, v[8:9]
	v_add_u32_e32 v70, 32, v70
	v_pk_add_f32 v[2:3], v[2:3], 0 neg_lo:[1,1] neg_hi:[1,1]
	s_nop 0
	v_and_b32_sdwa v10, v3, v115 dst_sel:DWORD dst_unused:UNUSED_PAD src0_sel:WORD_1 src1_sel:DWORD
	v_and_b32_sdwa v11, v2, v115 dst_sel:DWORD dst_unused:UNUSED_PAD src0_sel:WORD_1 src1_sel:DWORD
	v_add3_u32 v3, v3, v10, s82
	v_add3_u32 v2, v2, v11, s82
	v_and_b32_e32 v3, 0xffff0000, v3
	v_and_b32_e32 v2, 0xffff0000, v2
	v_or_b32_sdwa v1, v3, v1 dst_sel:DWORD dst_unused:UNUSED_PAD src0_sel:DWORD src1_sel:WORD_1
	v_or_b32_sdwa v0, v2, v0 dst_sel:DWORD dst_unused:UNUSED_PAD src0_sel:DWORD src1_sel:WORD_1
	global_store_dwordx2 v[8:9], v[0:1], off
	global_load_dwordx4 v[12:15], v[4:5], off
	v_add_u32_e32 v0, s6, v108
	ds_read_b128 v[8:11], v0
	s_waitcnt vmcnt(0) lgkmcnt(0)
	v_add_f32_e32 v0, v8, v12
	v_mul_f32_e32 v1, 0xbfb8aa3b, v0
	v_exp_f32_e32 v1, v1
	s_nop 0
	v_add_f32_e32 v1, 1.0, v1
	v_rcp_f32_e32 v1, v1
	s_nop 0
	s_nop 0
	s_nop 1
	s_nop 0
	s_nop 1
	v_mul_f32_e32 v0, 0x3f1b4598, v1
	v_add_f32_e32 v1, v9, v13
	v_mul_f32_e32 v2, 0xbfb8aa3b, v1
	v_exp_f32_e32 v2, v2
	s_nop 0
	v_add_f32_e32 v2, 1.0, v2
	v_rcp_f32_e32 v2, v2
	s_nop 0
	s_nop 1
	s_nop 0
	s_nop 1
	v_mul_f32_e32 v1, 0x3f1b4598, v2
	v_mov_b32_e32 v2, v1
	v_add_f32_e32 v1, v10, v14
	v_mul_f32_e32 v3, 0xbfb8aa3b, v1
	v_exp_f32_e32 v3, v3
	s_nop 0
	v_add_f32_e32 v3, 1.0, v3
	v_rcp_f32_e32 v3, v3
	s_nop 0
	s_nop 0
	s_nop 1
	s_nop 0
	s_nop 1
	v_mul_f32_e32 v1, 0x3f1b4598, v3
	v_add_f32_e32 v3, v11, v15
	v_mul_f32_e32 v8, 0xbfb8aa3b, v3
	v_exp_f32_e32 v8, v8
	s_nop 0
	v_add_f32_e32 v8, 1.0, v8
	v_rcp_f32_e32 v8, v8
	s_nop 0
	v_pk_add_f32 v[0:1], v[0:1], 0 neg_lo:[1,1] neg_hi:[1,1]
	s_nop 0
	v_and_b32_sdwa v10, v1, v115 dst_sel:DWORD dst_unused:UNUSED_PAD src0_sel:WORD_1 src1_sel:DWORD
	v_and_b32_sdwa v11, v0, v115 dst_sel:DWORD dst_unused:UNUSED_PAD src0_sel:WORD_1 src1_sel:DWORD
	v_add3_u32 v0, v0, v11, s82
	v_add3_u32 v1, v1, v10, s82
	s_nop 0
	v_mul_f32_e32 v3, 0x3f1b4598, v8
	v_lshlrev_b64 v[8:9], 10, v[68:69]
	v_lshl_add_u64 v[8:9], v[6:7], 0, v[8:9]
	v_add_u32_e32 v68, 32, v68
	v_pk_add_f32 v[2:3], v[2:3], 0 neg_lo:[1,1] neg_hi:[1,1]
	s_nop 0
	v_and_b32_sdwa v10, v3, v115 dst_sel:DWORD dst_unused:UNUSED_PAD src0_sel:WORD_1 src1_sel:DWORD
	v_and_b32_sdwa v11, v2, v115 dst_sel:DWORD dst_unused:UNUSED_PAD src0_sel:WORD_1 src1_sel:DWORD
	v_add3_u32 v3, v3, v10, s82
	v_add3_u32 v2, v2, v11, s82
	v_and_b32_e32 v3, 0xffff0000, v3
	v_and_b32_e32 v2, 0xffff0000, v2
	v_or_b32_sdwa v1, v3, v1 dst_sel:DWORD dst_unused:UNUSED_PAD src0_sel:DWORD src1_sel:WORD_1
	v_or_b32_sdwa v0, v2, v0 dst_sel:DWORD dst_unused:UNUSED_PAD src0_sel:DWORD src1_sel:WORD_1
	global_store_dwordx2 v[8:9], v[0:1], off
	global_load_dwordx4 v[12:15], v[4:5], off
	v_add_u32_e32 v0, s6, v99
	ds_read_b128 v[8:11], v0
	s_waitcnt vmcnt(0) lgkmcnt(0)
	v_add_f32_e32 v0, v8, v12
	v_mul_f32_e32 v1, 0xbfb8aa3b, v0
	v_exp_f32_e32 v1, v1
	s_nop 0
	v_add_f32_e32 v1, 1.0, v1
	v_rcp_f32_e32 v1, v1
	s_nop 0
	s_nop 0
	s_nop 1
	s_nop 0
	s_nop 1
	v_mul_f32_e32 v0, 0x3f1b4598, v1
	v_add_f32_e32 v1, v9, v13
	v_mul_f32_e32 v2, 0xbfb8aa3b, v1
	v_exp_f32_e32 v2, v2
	s_nop 0
	v_add_f32_e32 v2, 1.0, v2
	v_rcp_f32_e32 v2, v2
	s_nop 0
	s_nop 1
	s_nop 0
	s_nop 1
	v_mul_f32_e32 v1, 0x3f1b4598, v2
	v_mov_b32_e32 v2, v1
	v_add_f32_e32 v1, v10, v14
	v_mul_f32_e32 v3, 0xbfb8aa3b, v1
	v_exp_f32_e32 v3, v3
	s_nop 0
	v_add_f32_e32 v3, 1.0, v3
	v_rcp_f32_e32 v3, v3
	s_nop 0
	s_nop 0
	s_nop 1
	s_nop 0
	s_nop 1
	v_mul_f32_e32 v1, 0x3f1b4598, v3
	v_add_f32_e32 v3, v11, v15
	v_mul_f32_e32 v8, 0xbfb8aa3b, v3
	v_exp_f32_e32 v8, v8
	s_nop 0
	v_add_f32_e32 v8, 1.0, v8
	v_rcp_f32_e32 v8, v8
	s_nop 0
	v_pk_add_f32 v[0:1], v[0:1], 0 neg_lo:[1,1] neg_hi:[1,1]
	s_nop 0
	v_and_b32_sdwa v10, v1, v115 dst_sel:DWORD dst_unused:UNUSED_PAD src0_sel:WORD_1 src1_sel:DWORD
	v_and_b32_sdwa v11, v0, v115 dst_sel:DWORD dst_unused:UNUSED_PAD src0_sel:WORD_1 src1_sel:DWORD
	v_add3_u32 v0, v0, v11, s82
	v_add3_u32 v1, v1, v10, s82
	s_nop 0
	v_mul_f32_e32 v3, 0x3f1b4598, v8
	v_lshlrev_b64 v[8:9], 10, v[66:67]
	v_lshl_add_u64 v[8:9], v[6:7], 0, v[8:9]
	v_add_u32_e32 v66, 32, v66
	v_pk_add_f32 v[2:3], v[2:3], 0 neg_lo:[1,1] neg_hi:[1,1]
	s_nop 0
	v_and_b32_sdwa v10, v3, v115 dst_sel:DWORD dst_unused:UNUSED_PAD src0_sel:WORD_1 src1_sel:DWORD
	v_and_b32_sdwa v11, v2, v115 dst_sel:DWORD dst_unused:UNUSED_PAD src0_sel:WORD_1 src1_sel:DWORD
	v_add3_u32 v3, v3, v10, s82
	v_add3_u32 v2, v2, v11, s82
	v_and_b32_e32 v3, 0xffff0000, v3
	v_and_b32_e32 v2, 0xffff0000, v2
	v_or_b32_sdwa v1, v3, v1 dst_sel:DWORD dst_unused:UNUSED_PAD src0_sel:DWORD src1_sel:WORD_1
	v_or_b32_sdwa v0, v2, v0 dst_sel:DWORD dst_unused:UNUSED_PAD src0_sel:DWORD src1_sel:WORD_1
	global_store_dwordx2 v[8:9], v[0:1], off
	global_load_dwordx4 v[8:11], v[4:5], off
	v_add_u32_e32 v0, s6, v95
	ds_read_b128 v[0:3], v0
	s_addk_i32 s6, 0x4200
	s_cmp_lg_u32 s6, 0x10800
	s_waitcnt vmcnt(0) lgkmcnt(0)
	v_add_f32_e32 v0, v0, v8
	v_mul_f32_e32 v8, 0xbfb8aa3b, v0
	v_exp_f32_e32 v8, v8
	s_nop 0
	v_add_f32_e32 v8, 1.0, v8
	v_rcp_f32_e32 v8, v8
	s_nop 0
	v_add_f32_e32 v1, v1, v9
	s_nop 1
	s_nop 0
	s_nop 1
	v_mul_f32_e32 v0, 0x3f1b4598, v8
	v_mul_f32_e32 v8, 0xbfb8aa3b, v1
	v_exp_f32_e32 v8, v8
	s_nop 0
	v_add_f32_e32 v8, 1.0, v8
	v_rcp_f32_e32 v8, v8
	s_nop 0
	s_nop 1
	s_nop 0
	s_nop 1
	v_mul_f32_e32 v1, 0x3f1b4598, v8
	v_mov_b32_e32 v8, v1
	v_add_f32_e32 v1, v2, v10
	v_mul_f32_e32 v2, 0xbfb8aa3b, v1
	v_exp_f32_e32 v2, v2
	s_nop 0
	v_add_f32_e32 v2, 1.0, v2
	v_rcp_f32_e32 v2, v2
	s_nop 0
	s_nop 0
	s_nop 1
	s_nop 0
	s_nop 1
	v_mul_f32_e32 v1, 0x3f1b4598, v2
	v_add_f32_e32 v2, v3, v11
	v_mul_f32_e32 v3, 0xbfb8aa3b, v2
	v_exp_f32_e32 v3, v3
	s_nop 0
	v_add_f32_e32 v3, 1.0, v3
	v_rcp_f32_e32 v3, v3
	s_nop 0
	v_pk_add_f32 v[0:1], v[0:1], 0 neg_lo:[1,1] neg_hi:[1,1]
	s_nop 0
	v_and_b32_sdwa v10, v1, v115 dst_sel:DWORD dst_unused:UNUSED_PAD src0_sel:WORD_1 src1_sel:DWORD
	v_and_b32_sdwa v11, v0, v115 dst_sel:DWORD dst_unused:UNUSED_PAD src0_sel:WORD_1 src1_sel:DWORD
	v_add3_u32 v0, v0, v11, s82
	v_add3_u32 v1, v1, v10, s82
	s_nop 0
	v_mul_f32_e32 v2, 0x3f1b4598, v3
	v_mov_b32_e32 v9, v2
	v_lshlrev_b64 v[2:3], 10, v[64:65]
	v_lshl_add_u64 v[2:3], v[6:7], 0, v[2:3]
	v_add_u32_e32 v64, 32, v64
	v_pk_add_f32 v[8:9], v[8:9], 0 neg_lo:[1,1] neg_hi:[1,1]
	s_nop 0
	v_and_b32_sdwa v10, v9, v115 dst_sel:DWORD dst_unused:UNUSED_PAD src0_sel:WORD_1 src1_sel:DWORD
	v_and_b32_sdwa v11, v8, v115 dst_sel:DWORD dst_unused:UNUSED_PAD src0_sel:WORD_1 src1_sel:DWORD
	v_add3_u32 v9, v9, v10, s82
	v_add3_u32 v8, v8, v11, s82
	v_and_b32_e32 v9, 0xffff0000, v9
	v_and_b32_e32 v8, 0xffff0000, v8
	v_or_b32_sdwa v1, v9, v1 dst_sel:DWORD dst_unused:UNUSED_PAD src0_sel:DWORD src1_sel:WORD_1
	v_or_b32_sdwa v0, v8, v0 dst_sel:DWORD dst_unused:UNUSED_PAD src0_sel:DWORD src1_sel:WORD_1
	global_store_dwordx2 v[2:3], v[0:1], off
	s_cbranch_scc1 .LBB0_302
	s_add_i32 s0, s0, s33
	s_add_i32 s1, s1, s80
	s_cmpk_lt_i32 s0, 0x220
	s_barrier
	s_cbranch_scc1 .LBB0_277
